# speedup vs baseline: 1.0415x; 1.0177x over previous
; __device__ __forceinline__ void tr_job(float* lds, int& gt, const float* __restrict__ src, int src_ld, const float* __restrict__ gain,
;                        u16* __restrict__ dst, int dst_ld, int K, int Nvalid, int Ndst) {
;     ...
; #pragma unroll 16
;     for (int u = 0; u < 32; ++u) {
;       const int k = 2 * u + half, gk = k0 + k;
;       const int gkc = gk < K ? gk : K - 1;
;       float v = src[(size_t)gkc * src_ld + gnc];
;       if (gain) v *= gain[gkc];
;       wl[k * 33 + c] = (gk < K && gn < Nvalid) ? v : 0.f;
;     }
.LBB0_15:
	v_add_u32_e32 v10, s6, v5
	s_and_b64 vcc, exec, s[0:1]
	s_cbranch_vccnz .Lmy_tra_nog
	v_ashrrev_i32_e32 v11, 31, v10
	v_lshl_add_u64 v[18:19], v[10:11], 2, s[56:57]
	global_load_dword v216, v[18:19], off
	global_load_dword v217, v[18:19], off offset:8
	global_load_dword v218, v[18:19], off offset:16
	global_load_dword v219, v[18:19], off offset:24
	global_load_dword v220, v[18:19], off offset:32
	global_load_dword v221, v[18:19], off offset:40
	global_load_dword v222, v[18:19], off offset:48
	global_load_dword v223, v[18:19], off offset:56
	global_load_dword v224, v[18:19], off offset:64
	global_load_dword v225, v[18:19], off offset:72
	global_load_dword v226, v[18:19], off offset:80
	global_load_dword v227, v[18:19], off offset:88
	global_load_dword v228, v[18:19], off offset:96
	global_load_dword v229, v[18:19], off offset:104
	global_load_dword v230, v[18:19], off offset:112
	global_load_dword v231, v[18:19], off offset:120
	s_branch .Lmy_tra_data
.Lmy_tra_nog:
	v_mov_b32_e32 v216, 1.0
	v_mov_b32_e32 v217, 1.0
	v_mov_b32_e32 v218, 1.0
	v_mov_b32_e32 v219, 1.0
	v_mov_b32_e32 v220, 1.0
	v_mov_b32_e32 v221, 1.0
	v_mov_b32_e32 v222, 1.0
	v_mov_b32_e32 v223, 1.0
	v_mov_b32_e32 v224, 1.0
	v_mov_b32_e32 v225, 1.0
	v_mov_b32_e32 v226, 1.0
	v_mov_b32_e32 v227, 1.0
	v_mov_b32_e32 v228, 1.0
	v_mov_b32_e32 v229, 1.0
	v_mov_b32_e32 v230, 1.0
	v_mov_b32_e32 v231, 1.0
.Lmy_tra_data:
	v_mad_i64_i32 v[18:19], s[86:87], v10, s82, v[6:7]
	global_load_dword v200, v[18:19], off
	v_add_u32_e32 v11, 2, v10
	v_mad_i64_i32 v[18:19], s[86:87], v11, s82, v[6:7]
	global_load_dword v201, v[18:19], off
	v_add_u32_e32 v11, 4, v10
	v_mad_i64_i32 v[18:19], s[86:87], v11, s82, v[6:7]
	global_load_dword v202, v[18:19], off
	v_add_u32_e32 v11, 6, v10
	v_mad_i64_i32 v[18:19], s[86:87], v11, s82, v[6:7]
	global_load_dword v203, v[18:19], off
	v_add_u32_e32 v11, 8, v10
	v_mad_i64_i32 v[18:19], s[86:87], v11, s82, v[6:7]
	global_load_dword v204, v[18:19], off
	v_add_u32_e32 v11, 10, v10
	v_mad_i64_i32 v[18:19], s[86:87], v11, s82, v[6:7]
	global_load_dword v205, v[18:19], off
	v_add_u32_e32 v11, 12, v10
	v_mad_i64_i32 v[18:19], s[86:87], v11, s82, v[6:7]
	global_load_dword v206, v[18:19], off
	v_add_u32_e32 v11, 14, v10
	v_mad_i64_i32 v[18:19], s[86:87], v11, s82, v[6:7]
	global_load_dword v207, v[18:19], off
	v_add_u32_e32 v11, 16, v10
	v_mad_i64_i32 v[18:19], s[86:87], v11, s82, v[6:7]
	global_load_dword v208, v[18:19], off
	v_add_u32_e32 v11, 18, v10
	v_mad_i64_i32 v[18:19], s[86:87], v11, s82, v[6:7]
	global_load_dword v209, v[18:19], off
	v_add_u32_e32 v11, 20, v10
	v_mad_i64_i32 v[18:19], s[86:87], v11, s82, v[6:7]
	global_load_dword v210, v[18:19], off
	v_add_u32_e32 v11, 22, v10
	v_mad_i64_i32 v[18:19], s[86:87], v11, s82, v[6:7]
	global_load_dword v211, v[18:19], off
	v_add_u32_e32 v11, 24, v10
	v_mad_i64_i32 v[18:19], s[86:87], v11, s82, v[6:7]
	global_load_dword v212, v[18:19], off
	v_add_u32_e32 v11, 26, v10
	v_mad_i64_i32 v[18:19], s[86:87], v11, s82, v[6:7]
	global_load_dword v213, v[18:19], off
	v_add_u32_e32 v11, 28, v10
	v_mad_i64_i32 v[18:19], s[86:87], v11, s82, v[6:7]
	global_load_dword v214, v[18:19], off
	v_add_u32_e32 v11, 30, v10
	v_mad_i64_i32 v[18:19], s[86:87], v11, s82, v[6:7]
	global_load_dword v215, v[18:19], off
	s_waitcnt vmcnt(15)
	v_mul_f32_e32 v200, v200, v216
	v_cndmask_b32_e64 v200, 0, v200, s[4:5]
	ds_write_b32 v12, v200
	s_waitcnt vmcnt(14)
	v_mul_f32_e32 v201, v201, v217
	v_cndmask_b32_e64 v201, 0, v201, s[4:5]
	ds_write_b32 v12, v201 offset:264
	s_waitcnt vmcnt(13)
	v_mul_f32_e32 v202, v202, v218
	v_cndmask_b32_e64 v202, 0, v202, s[4:5]
	ds_write_b32 v12, v202 offset:528
	s_waitcnt vmcnt(12)
	v_mul_f32_e32 v203, v203, v219
	v_cndmask_b32_e64 v203, 0, v203, s[4:5]
	ds_write_b32 v12, v203 offset:792
	s_waitcnt vmcnt(11)
	v_mul_f32_e32 v204, v204, v220
	v_cndmask_b32_e64 v204, 0, v204, s[4:5]
	ds_write_b32 v12, v204 offset:1056
	s_waitcnt vmcnt(10)
	v_mul_f32_e32 v205, v205, v221
	v_cndmask_b32_e64 v205, 0, v205, s[4:5]
	ds_write_b32 v12, v205 offset:1320
	s_waitcnt vmcnt(9)
	v_mul_f32_e32 v206, v206, v222
	v_cndmask_b32_e64 v206, 0, v206, s[4:5]
	ds_write_b32 v12, v206 offset:1584
	s_waitcnt vmcnt(8)
	v_mul_f32_e32 v207, v207, v223
	v_cndmask_b32_e64 v207, 0, v207, s[4:5]
	ds_write_b32 v12, v207 offset:1848
	s_waitcnt vmcnt(7)
	v_mul_f32_e32 v208, v208, v224
	v_cndmask_b32_e64 v208, 0, v208, s[4:5]
	ds_write_b32 v12, v208 offset:2112
	s_waitcnt vmcnt(6)
	v_mul_f32_e32 v209, v209, v225
	v_cndmask_b32_e64 v209, 0, v209, s[4:5]
	ds_write_b32 v12, v209 offset:2376
	s_waitcnt vmcnt(5)
	v_mul_f32_e32 v210, v210, v226
	v_cndmask_b32_e64 v210, 0, v210, s[4:5]
	ds_write_b32 v12, v210 offset:2640
	s_waitcnt vmcnt(4)
	v_mul_f32_e32 v211, v211, v227
	v_cndmask_b32_e64 v211, 0, v211, s[4:5]
	ds_write_b32 v12, v211 offset:2904
	s_waitcnt vmcnt(3)
	v_mul_f32_e32 v212, v212, v228
	v_cndmask_b32_e64 v212, 0, v212, s[4:5]
	ds_write_b32 v12, v212 offset:3168
	s_waitcnt vmcnt(2)
	v_mul_f32_e32 v213, v213, v229
	v_cndmask_b32_e64 v213, 0, v213, s[4:5]
	ds_write_b32 v12, v213 offset:3432
	s_waitcnt vmcnt(1)
	v_mul_f32_e32 v214, v214, v230
	v_cndmask_b32_e64 v214, 0, v214, s[4:5]
	ds_write_b32 v12, v214 offset:3696
	s_waitcnt vmcnt(0)
	v_mul_f32_e32 v215, v215, v231
	v_cndmask_b32_e64 v215, 0, v215, s[4:5]
	ds_write_b32 v12, v215 offset:3960
	s_add_i32 s6, s6, 32
	v_add_u32_e32 v12, 0x1080, v12
	s_cmp_eq_u32 s6, 64
	s_cbranch_scc0 .LBB0_15

; __device__ __forceinline__ void tr_job(float* lds, int& gt, const float* __restrict__ src, int src_ld, const float* __restrict__ gain,
;                        u16* __restrict__ dst, int dst_ld, int K, int Nvalid, int Ndst) {
;     ...
; #pragma unroll 16
;     for (int u = 0; u < 32; ++u) {
;       const int k = 2 * u + half, gk = k0 + k;
;       const int gkc = gk < K ? gk : K - 1;
;       float v = src[(size_t)gkc * src_ld + gnc];
;       if (gain) v *= gain[gkc];
;       wl[k * 33 + c] = (gk < K && gn < Nvalid) ? v : 0.f;
;     }
.Lmy_trb_data:
	v_mad_i64_i32 v[18:19], s[84:85], v10, s80, v[6:7]
	global_load_dword v200, v[18:19], off
	v_add_u32_e32 v11, 2, v10
	v_mad_i64_i32 v[18:19], s[84:85], v11, s80, v[6:7]
	global_load_dword v201, v[18:19], off
	v_add_u32_e32 v11, 4, v10
	v_mad_i64_i32 v[18:19], s[84:85], v11, s80, v[6:7]
	global_load_dword v202, v[18:19], off
	v_add_u32_e32 v11, 6, v10
	v_mad_i64_i32 v[18:19], s[84:85], v11, s80, v[6:7]
	global_load_dword v203, v[18:19], off
	v_add_u32_e32 v11, 8, v10
	v_mad_i64_i32 v[18:19], s[84:85], v11, s80, v[6:7]
	global_load_dword v204, v[18:19], off
	v_add_u32_e32 v11, 10, v10
	v_mad_i64_i32 v[18:19], s[84:85], v11, s80, v[6:7]
	global_load_dword v205, v[18:19], off
	v_add_u32_e32 v11, 12, v10
	v_mad_i64_i32 v[18:19], s[84:85], v11, s80, v[6:7]
	global_load_dword v206, v[18:19], off
	v_add_u32_e32 v11, 14, v10
	v_mad_i64_i32 v[18:19], s[84:85], v11, s80, v[6:7]
	global_load_dword v207, v[18:19], off
	v_add_u32_e32 v11, 16, v10
	v_mad_i64_i32 v[18:19], s[84:85], v11, s80, v[6:7]
	global_load_dword v208, v[18:19], off
	v_add_u32_e32 v11, 18, v10
	v_mad_i64_i32 v[18:19], s[84:85], v11, s80, v[6:7]
	global_load_dword v209, v[18:19], off
	v_add_u32_e32 v11, 20, v10
	v_mad_i64_i32 v[18:19], s[84:85], v11, s80, v[6:7]
	global_load_dword v210, v[18:19], off
	v_add_u32_e32 v11, 22, v10
	v_mad_i64_i32 v[18:19], s[84:85], v11, s80, v[6:7]
	global_load_dword v211, v[18:19], off
	v_add_u32_e32 v11, 24, v10
	v_mad_i64_i32 v[18:19], s[84:85], v11, s80, v[6:7]
	global_load_dword v212, v[18:19], off
	v_add_u32_e32 v11, 26, v10
	v_mad_i64_i32 v[18:19], s[84:85], v11, s80, v[6:7]
	global_load_dword v213, v[18:19], off
	v_add_u32_e32 v11, 28, v10
	v_mad_i64_i32 v[18:19], s[84:85], v11, s80, v[6:7]
	global_load_dword v214, v[18:19], off
	v_add_u32_e32 v11, 30, v10
	v_mad_i64_i32 v[18:19], s[84:85], v11, s80, v[6:7]
	global_load_dword v215, v[18:19], off
	s_waitcnt vmcnt(15)
	v_mul_f32_e32 v200, v200, v216
	v_cndmask_b32_e64 v200, 0, v200, s[4:5]
	ds_write_b32 v12, v200
	s_waitcnt vmcnt(14)
	v_mul_f32_e32 v201, v201, v217
	v_cndmask_b32_e64 v201, 0, v201, s[4:5]
	ds_write_b32 v12, v201 offset:264
	s_waitcnt vmcnt(13)
	v_mul_f32_e32 v202, v202, v218
	v_cndmask_b32_e64 v202, 0, v202, s[4:5]
	ds_write_b32 v12, v202 offset:528
	s_waitcnt vmcnt(12)
	v_mul_f32_e32 v203, v203, v219
	v_cndmask_b32_e64 v203, 0, v203, s[4:5]
	ds_write_b32 v12, v203 offset:792
	s_waitcnt vmcnt(11)
	v_mul_f32_e32 v204, v204, v220
	v_cndmask_b32_e64 v204, 0, v204, s[4:5]
	ds_write_b32 v12, v204 offset:1056
	s_waitcnt vmcnt(10)
	v_mul_f32_e32 v205, v205, v221
	v_cndmask_b32_e64 v205, 0, v205, s[4:5]
	ds_write_b32 v12, v205 offset:1320
	s_waitcnt vmcnt(9)
	v_mul_f32_e32 v206, v206, v222
	v_cndmask_b32_e64 v206, 0, v206, s[4:5]
	ds_write_b32 v12, v206 offset:1584
	s_waitcnt vmcnt(8)
	v_mul_f32_e32 v207, v207, v223
	v_cndmask_b32_e64 v207, 0, v207, s[4:5]
	ds_write_b32 v12, v207 offset:1848
	s_waitcnt vmcnt(7)
	v_mul_f32_e32 v208, v208, v224
	v_cndmask_b32_e64 v208, 0, v208, s[4:5]
	ds_write_b32 v12, v208 offset:2112
	s_waitcnt vmcnt(6)
	v_mul_f32_e32 v209, v209, v225
	v_cndmask_b32_e64 v209, 0, v209, s[4:5]
	ds_write_b32 v12, v209 offset:2376
	s_waitcnt vmcnt(5)
	v_mul_f32_e32 v210, v210, v226
	v_cndmask_b32_e64 v210, 0, v210, s[4:5]
	ds_write_b32 v12, v210 offset:2640
	s_waitcnt vmcnt(4)
	v_mul_f32_e32 v211, v211, v227
	v_cndmask_b32_e64 v211, 0, v211, s[4:5]
	ds_write_b32 v12, v211 offset:2904
	s_waitcnt vmcnt(3)
	v_mul_f32_e32 v212, v212, v228
	v_cndmask_b32_e64 v212, 0, v212, s[4:5]
	ds_write_b32 v12, v212 offset:3168
	s_waitcnt vmcnt(2)
	v_mul_f32_e32 v213, v213, v229
	v_cndmask_b32_e64 v213, 0, v213, s[4:5]
	ds_write_b32 v12, v213 offset:3432
	s_waitcnt vmcnt(1)
	v_mul_f32_e32 v214, v214, v230
	v_cndmask_b32_e64 v214, 0, v214, s[4:5]
	ds_write_b32 v12, v214 offset:3696
	s_waitcnt vmcnt(0)
	v_mul_f32_e32 v215, v215, v231
	v_cndmask_b32_e64 v215, 0, v215, s[4:5]
	ds_write_b32 v12, v215 offset:3960
	s_add_i32 s6, s6, 32
	v_add_u32_e32 v12, 0x1080, v12
	s_cmp_eq_u32 s6, 64
	s_cbranch_scc0 .LBB0_120

; __device__ __forceinline__ void tr_job(float* lds, int& gt, const float* __restrict__ src, int src_ld, const float* __restrict__ gain,
;                        u16* __restrict__ dst, int dst_ld, int K, int Nvalid, int Ndst) {
;     ...
; #pragma unroll 16
;     for (int u = 0; u < 32; ++u) {
;       const int k = 2 * u + half, gk = k0 + k;
;       const int gkc = gk < K ? gk : K - 1;
;       float v = src[(size_t)gkc * src_ld + gnc];
;       if (gain) v *= gain[gkc];
.LBB0_317:
	v_add_u32_e32 v10, s6, v5
	s_and_b64 vcc, exec, s[0:1]
	s_cbranch_vccnz .Lmy_trc_nog
	v_ashrrev_i32_e32 v11, 31, v10
	v_lshl_add_u64 v[18:19], v[10:11], 2, s[64:65]
	global_load_dword v216, v[18:19], off
	global_load_dword v217, v[18:19], off offset:8
	global_load_dword v218, v[18:19], off offset:16
	global_load_dword v219, v[18:19], off offset:24
	global_load_dword v220, v[18:19], off offset:32
	global_load_dword v221, v[18:19], off offset:40
	global_load_dword v222, v[18:19], off offset:48
	global_load_dword v223, v[18:19], off offset:56
	global_load_dword v224, v[18:19], off offset:64
	global_load_dword v225, v[18:19], off offset:72
	global_load_dword v226, v[18:19], off offset:80
	global_load_dword v227, v[18:19], off offset:88
	global_load_dword v228, v[18:19], off offset:96
	global_load_dword v229, v[18:19], off offset:104
	global_load_dword v230, v[18:19], off offset:112
	global_load_dword v231, v[18:19], off offset:120
	s_branch .Lmy_trc_data

; __device__ __forceinline__ void tr_job(float* lds, int& gt, const float* __restrict__ src, int src_ld, const float* __restrict__ gain,
;                        u16* __restrict__ dst, int dst_ld, int K, int Nvalid, int Ndst) {
;     ...
;   for (int i = first; i < nt; i += NW) {
;     const int k0 = (i % tk) * 64, n0 = (i / tk) * 32;
;     const int gn = n0 + c;
;     const int gnc = gn < Nvalid ? gn : Nvalid - 1;
; #pragma unroll 16
;     for (int u = 0; u < 32; ++u) {
;       const int k = 2 * u + half, gk = k0 + k;
;       const int gkc = gk < K ? gk : K - 1;
;       float v = src[(size_t)gkc * src_ld + gnc];
;       if (gain) v *= gain[gkc];
;       wl[k * 33 + c] = (gk < K && gn < Nvalid) ? v : 0.f;
;     }
.Lmy_trc_data:
	v_mad_i64_i32 v[18:19], s[80:81], v10, s59, v[6:7]
	global_load_dword v200, v[18:19], off
	v_add_u32_e32 v11, 2, v10
	v_mad_i64_i32 v[18:19], s[80:81], v11, s59, v[6:7]
	global_load_dword v201, v[18:19], off
	v_add_u32_e32 v11, 4, v10
	v_mad_i64_i32 v[18:19], s[80:81], v11, s59, v[6:7]
	global_load_dword v202, v[18:19], off
	v_add_u32_e32 v11, 6, v10
	v_mad_i64_i32 v[18:19], s[80:81], v11, s59, v[6:7]
	global_load_dword v203, v[18:19], off
	v_add_u32_e32 v11, 8, v10
	v_mad_i64_i32 v[18:19], s[80:81], v11, s59, v[6:7]
	global_load_dword v204, v[18:19], off
	v_add_u32_e32 v11, 10, v10
	v_mad_i64_i32 v[18:19], s[80:81], v11, s59, v[6:7]
	global_load_dword v205, v[18:19], off
	v_add_u32_e32 v11, 12, v10
	v_mad_i64_i32 v[18:19], s[80:81], v11, s59, v[6:7]
	global_load_dword v206, v[18:19], off
	v_add_u32_e32 v11, 14, v10
	v_mad_i64_i32 v[18:19], s[80:81], v11, s59, v[6:7]
	global_load_dword v207, v[18:19], off
	v_add_u32_e32 v11, 16, v10
	v_mad_i64_i32 v[18:19], s[80:81], v11, s59, v[6:7]
	global_load_dword v208, v[18:19], off
	v_add_u32_e32 v11, 18, v10
	v_mad_i64_i32 v[18:19], s[80:81], v11, s59, v[6:7]
	global_load_dword v209, v[18:19], off
	v_add_u32_e32 v11, 20, v10
	v_mad_i64_i32 v[18:19], s[80:81], v11, s59, v[6:7]
	global_load_dword v210, v[18:19], off
	v_add_u32_e32 v11, 22, v10
	v_mad_i64_i32 v[18:19], s[80:81], v11, s59, v[6:7]
	global_load_dword v211, v[18:19], off
	v_add_u32_e32 v11, 24, v10
	v_mad_i64_i32 v[18:19], s[80:81], v11, s59, v[6:7]
	global_load_dword v212, v[18:19], off
	v_add_u32_e32 v11, 26, v10
	v_mad_i64_i32 v[18:19], s[80:81], v11, s59, v[6:7]
	global_load_dword v213, v[18:19], off
	v_add_u32_e32 v11, 28, v10
	v_mad_i64_i32 v[18:19], s[80:81], v11, s59, v[6:7]
	global_load_dword v214, v[18:19], off
	v_add_u32_e32 v11, 30, v10
	v_mad_i64_i32 v[18:19], s[80:81], v11, s59, v[6:7]
	global_load_dword v215, v[18:19], off
	s_waitcnt vmcnt(15)
	v_mul_f32_e32 v200, v200, v216
	v_cndmask_b32_e64 v200, 0, v200, s[4:5]
	ds_write_b32 v12, v200
	s_waitcnt vmcnt(14)
	v_mul_f32_e32 v201, v201, v217
	v_cndmask_b32_e64 v201, 0, v201, s[4:5]
	ds_write_b32 v12, v201 offset:264
	s_waitcnt vmcnt(13)
	v_mul_f32_e32 v202, v202, v218
	v_cndmask_b32_e64 v202, 0, v202, s[4:5]
	ds_write_b32 v12, v202 offset:528
	s_waitcnt vmcnt(12)
	v_mul_f32_e32 v203, v203, v219
	v_cndmask_b32_e64 v203, 0, v203, s[4:5]
	ds_write_b32 v12, v203 offset:792
	s_waitcnt vmcnt(11)
	v_mul_f32_e32 v204, v204, v220
	v_cndmask_b32_e64 v204, 0, v204, s[4:5]
	ds_write_b32 v12, v204 offset:1056
	s_waitcnt vmcnt(10)
	v_mul_f32_e32 v205, v205, v221
	v_cndmask_b32_e64 v205, 0, v205, s[4:5]
	ds_write_b32 v12, v205 offset:1320
	s_waitcnt vmcnt(9)
	v_mul_f32_e32 v206, v206, v222
	v_cndmask_b32_e64 v206, 0, v206, s[4:5]
	ds_write_b32 v12, v206 offset:1584
	s_waitcnt vmcnt(8)
	v_mul_f32_e32 v207, v207, v223
	v_cndmask_b32_e64 v207, 0, v207, s[4:5]
	ds_write_b32 v12, v207 offset:1848
	s_waitcnt vmcnt(7)
	v_mul_f32_e32 v208, v208, v224
	v_cndmask_b32_e64 v208, 0, v208, s[4:5]
	ds_write_b32 v12, v208 offset:2112
	s_waitcnt vmcnt(6)
	v_mul_f32_e32 v209, v209, v225
	v_cndmask_b32_e64 v209, 0, v209, s[4:5]
	ds_write_b32 v12, v209 offset:2376
	s_waitcnt vmcnt(5)
	v_mul_f32_e32 v210, v210, v226
	v_cndmask_b32_e64 v210, 0, v210, s[4:5]
	ds_write_b32 v12, v210 offset:2640
	s_waitcnt vmcnt(4)
	v_mul_f32_e32 v211, v211, v227
	v_cndmask_b32_e64 v211, 0, v211, s[4:5]
	ds_write_b32 v12, v211 offset:2904
	s_waitcnt vmcnt(3)
	v_mul_f32_e32 v212, v212, v228
	v_cndmask_b32_e64 v212, 0, v212, s[4:5]
	ds_write_b32 v12, v212 offset:3168
	s_waitcnt vmcnt(2)
	v_mul_f32_e32 v213, v213, v229
	v_cndmask_b32_e64 v213, 0, v213, s[4:5]
	ds_write_b32 v12, v213 offset:3432
	s_waitcnt vmcnt(1)
	v_mul_f32_e32 v214, v214, v230
	v_cndmask_b32_e64 v214, 0, v214, s[4:5]
	ds_write_b32 v12, v214 offset:3696
	s_waitcnt vmcnt(0)
	v_mul_f32_e32 v215, v215, v231
	v_cndmask_b32_e64 v215, 0, v215, s[4:5]
	ds_write_b32 v12, v215 offset:3960
	s_add_i32 s6, s6, 32
	v_add_u32_e32 v12, 0x1080, v12
	s_cmp_eq_u32 s6, 64
	s_cbranch_scc0 .LBB0_317

; __device__ __forceinline__ int opaque_tid() { int t; asm volatile("v_mov_b32 %0, %1" : "=v"(t) : "v"((int)threadIdx.x)); return t; }
; template <int NS, bool LORA, int mat> ...
;     ...
;   const int ch = 64 * head + lane;
;   const float kk_c = p.k_k[ch], ka_c = p.k_a[ch], rk_c = p.r_k[ch];
;   const float mu_r = p.mu_shift[ch], mu_k = p.mu_shift[1024 + ch], mu_v = p.mu_shift[2048 + ch];
; template <int RG, int NSW>
; __device__ __forceinline__ void scan_job(const Params& p, float* lds, const size_t tok0, const int T, const int head,
;                                          const int dir, const int row_base, const int rk_sel) {
;   const int tidx = opaque_tid();
;   const int wave = tidx >> 6, lane = tidx & 63;
;   if (NSW == 4) {
;     if (wave < 4) scan_waves<RG, NSW>(p, lds, T, dir, wave, lane, tok0, head, row_base);
;     else if (wave == 4) prep_waves<1, true, 0>(p, lds, T, dir, lane, tok0, head, 0, rk_sel);
;     else if (wave == 5) prep_waves<3, true, 1>(p, lds, T, dir, lane, tok0, head, 1, rk_sel);
;     else prep_waves<6, false, 0>(p, lds, T, dir, lane, tok0, head, 4 + (wave - 6) * 6, rk_sel);
.LBB0_1226:
	s_andn2_b64 vcc, exec, s[0:1]
	s_cbranch_vccnz .LBB0_1354
	s_ashr_i32 s0, s2, 3
	s_add_i32 s4, s3, s0
	s_and_b32 s3, s0, 3
	s_ashr_i32 s59, s4, 3
	s_bfe_u32 s58, s0, 0x10002
	s_cmp_eq_u32 s58, 0
	s_waitcnt vmcnt(7)
	v_mov_b32 v140, v146
	s_cselect_b64 s[0:1], -1, 0
	s_waitcnt vmcnt(0)
	v_ashrrev_i32_e32 v6, 6, v140
	v_and_b32_e32 v148, 63, v140
	v_cmp_lt_i32_e32 vcc, 3, v6
	s_and_saveexec_b64 s[6:7], vcc
	s_xor_b64 s[46:47], exec, s[6:7]
	s_cbranch_execz .LBB0_1346
	s_lshl_b32 s61, s59, 6
	s_lshl_b32 s63, s58, 6
	s_lshl_b32 s5, s58, 10
	s_ashr_i32 s6, s61, 31
	s_add_u32 s64, s61, s5
	s_addc_u32 s65, s6, 0
	s_add_i32 s62, s61, s5
	s_and_b32 s4, s4, -8
	s_lshl_b32 s5, s58, 2
	s_or_b32 s60, s5, s4
	v_cmp_lt_i32_e32 vcc, 4, v6
	s_and_saveexec_b64 s[4:5], vcc
	s_xor_b64 s[48:49], exec, s[4:5]
	s_cbranch_execz .LBB0_1319
	v_cmp_ne_u32_e32 vcc, 5, v6
	s_and_saveexec_b64 s[4:5], vcc
	s_xor_b64 s[52:53], exec, s[4:5]
	s_cbranch_execz .LBB0_1276
	v_or_b32_e32 v8, s61, v148
	v_ashrrev_i32_e32 v9, 31, v8
	v_lshlrev_b64 v[4:5], 2, v[8:9]
	v_lshl_add_u64 v[0:1], s[50:51], 0, v[4:5]
	v_lshl_add_u64 v[2:3], s[16:17], 0, v[4:5]
	global_load_dword v0, v[0:1], off
	v_mul_lo_u32 v9, v6, 6
	global_load_dword v1, v[2:3], off
	v_lshl_add_u64 v[2:3], s[18:19], 0, v[4:5]
	v_lshl_add_u64 v[4:5], s[38:39], 0, v[4:5]
	v_add_co_u32_e32 v10, vcc, 0x1000, v4
	global_load_dword v2, v[2:3], off
	s_nop 0
	v_addc_co_u32_e32 v11, vcc, 0, v5, vcc
	v_add_co_u32_e32 v12, vcc, 0x2000, v4
	v_add_u32_e32 v6, 0x400, v8
	s_nop 0
	v_addc_co_u32_e32 v13, vcc, 0, v5, vcc
	global_load_dword v3, v[4:5], off
	global_load_dword v4, v[10:11], off
	global_load_dword v5, v[12:13], off
	v_add_u32_e32 v8, -16, v9
	s_movk_i32 s6, 0x500
	v_and_b32_e32 v11, 2, v9
	v_lshlrev_b32_e32 v10, 8, v8
	v_mul_lo_u32 v8, v8, s6
	v_cmp_eq_u32_e64 s[6:7], s3, v11
	v_subrev_u32_e32 v11, 31, v9
	v_and_b32_e32 v15, 3, v11
	v_cmp_eq_u32_e64 s[8:9], s3, v15
	v_subrev_u32_e32 v15, 30, v9
	v_and_b32_e32 v18, 2, v15
	v_cmp_eq_u32_e64 s[10:11], s3, v18
	v_subrev_u32_e32 v18, 29, v9
	v_subrev_u32_e32 v23, 27, v9
	v_lshlrev_b32_e32 v12, 8, v9
	v_and_b32_e32 v21, 3, v18
	v_and_b32_e32 v26, 3, v23
	v_lshl_add_u32 v7, v148, 2, 0
	v_add_u32_e32 v13, 0xfffff100, v12
	v_add_u32_e32 v14, 0x500, v8
	v_add_u32_e32 v16, 0xfffff200, v12
	v_add_u32_e32 v17, 0xa00, v8
	v_add_u32_e32 v19, 0xfffff300, v12
	v_add_u32_e32 v20, 0xf00, v8
	v_cmp_eq_u32_e64 s[12:13], s3, v21
	v_add_u32_e32 v21, 0xfffff400, v12
	v_add_u32_e32 v22, 0x1400, v8
	v_add_u32_e32 v24, 0xfffff500, v12
	v_add_u32_e32 v25, 0x1900, v8
	v_cmp_eq_u32_e64 s[14:15], s3, v26
	v_add_u32_e32 v26, 0xffffe000, v12
	v_add_u32_e32 v28, 0xffffb000, v8
	v_lshlrev_b32_e32 v27, 8, v11
	v_lshlrev_b32_e32 v29, 8, v15
	v_lshlrev_b32_e32 v30, 8, v18
	v_add_u32_e32 v31, 0xffffe400, v12
	v_lshlrev_b32_e32 v32, 8, v23
	v_cmp_eq_u32_e64 s[4:5], 0, v148
	v_subrev_u32_e32 v142, 48, v9
	v_sub_u32_e32 v141, 0x402f, v9
	s_mov_b32 s66, 1
	s_movk_i32 s67, 0xe00
	s_movk_i32 s77, 0x3fff
	v_add_u32_e32 v9, v7, v10
	v_add_u32_e32 v10, v7, v13
	v_add_u32_e32 v11, v7, v14
	v_add_u32_e32 v12, v7, v16
	v_add_u32_e32 v13, v7, v17
	v_add_u32_e32 v14, v7, v19
	v_add_u32_e32 v15, v7, v20
	v_add_u32_e32 v16, v7, v21
	v_add_u32_e32 v17, v7, v22
	v_add_u32_e32 v18, v7, v24
	v_add_u32_e32 v19, v7, v25
	v_add_u32_e32 v20, v7, v26
	v_add_u32_e32 v21, v7, v27
	v_add_u32_e32 v22, v7, v29
	v_add_u32_e32 v23, v7, v30
	v_add_u32_e32 v24, v7, v31
	v_add_u32_e32 v25, v7, v32
	v_mov_b32_e32 v26, 0xffffe400
	v_mov_b32_e32 v27, 0x1c00
	v_add_u32_e32 v28, v7, v28
	s_branch .LBB0_1233

.LBB0_1233:
	s_add_i32 s80, s66, -1
	s_cmpk_lt_u32 s80, 0x400
	v_add_u32_e32 v137, 16, v142
	v_add_u32_e32 v138, -16, v141
	v_add_u32_e32 v139, 17, v142
	v_subrev_u32_e32 v140, 17, v141
	v_add_u32_e32 v145, 18, v142
	v_subrev_u32_e32 v147, 18, v141
	v_add_u32_e32 v148, 19, v142
	v_subrev_u32_e32 v149, 19, v141
	v_add_u32_e32 v150, 20, v142
	v_subrev_u32_e32 v151, 20, v141
	v_add_u32_e32 v152, 21, v142
	v_subrev_u32_e32 v153, 21, v141
	s_cselect_b64 s[54:55], -1, 0
	s_cmpk_gt_u32 s80, 0x3ff
	v_cndmask_b32_e64 v144, v138, v137, s[0:1]
	v_cndmask_b32_e64 v143, v140, v139, s[0:1]
	v_cndmask_b32_e64 v140, v147, v145, s[0:1]
	v_cndmask_b32_e64 v139, v149, v148, s[0:1]
	v_cndmask_b32_e64 v138, v151, v150, s[0:1]
	v_cndmask_b32_e64 v137, v153, v152, s[0:1]
	s_cbranch_scc1 .Lmy_w6_t1
	s_waitcnt vmcnt(46)
	v_mul_lo_u32 v53, v144, s67
	v_cmp_lt_i32_e32 vcc, 0, v144
	v_add_lshl_u32 v53, v53, v6, 1
	v_add_u32_e32 v56, 0x800, v53
	v_cndmask_b32_e32 v54, 0, v26, vcc
	v_cmp_gt_i32_e32 vcc, s77, v144
	v_add_u32_e32 v54, v53, v54
	v_add_u32_e32 v57, 0xfffff800, v54
	v_cndmask_b32_e32 v55, 0, v27, vcc
	s_waitcnt vmcnt(38)
	v_add_u32_e32 v61, v53, v55
	v_add_u32_e32 v55, 0xfffff800, v53
	v_add_u32_e32 v62, 0x800, v54
	v_add_u32_e32 v63, 0xfffff800, v61
	global_load_ushort v60, v55, s[72:73]
	global_load_ushort v59, v53, s[72:73]
	global_load_ushort v58, v56, s[72:73]
	global_load_ushort v57, v57, s[72:73]
	global_load_ushort v56, v54, s[72:73]
	global_load_ushort v55, v62, s[72:73]
	global_load_ushort v54, v63, s[72:73]
	global_load_ushort v53, v61, s[72:73]
	v_mul_lo_u32 v62, v143, s67
	v_cmp_lt_i32_e32 vcc, 0, v143
	v_add_lshl_u32 v62, v62, v6, 1
	v_add_u32_e32 v61, 0x800, v61
	v_cndmask_b32_e32 v63, 0, v26, vcc
	v_cmp_gt_i32_e32 vcc, s77, v143
	v_add_u32_e32 v63, v62, v63
	v_add_u32_e32 v65, 0x800, v62
	v_cndmask_b32_e32 v64, 0, v27, vcc
	s_waitcnt vmcnt(38)
	v_add_u32_e32 v77, v62, v64
	v_add_u32_e32 v64, 0xfffff800, v62
	v_add_u32_e32 v78, 0xfffff800, v63
	v_add_u32_e32 v79, 0x800, v63
	global_load_ushort v68, v61, s[72:73]
	global_load_ushort v67, v64, s[72:73]
	global_load_ushort v66, v62, s[72:73]
	global_load_ushort v65, v65, s[72:73]
	global_load_ushort v64, v78, s[72:73]
	global_load_ushort v63, v63, s[72:73]
	global_load_ushort v62, v79, s[72:73]
	global_load_ushort v61, v77, s[72:73]
	v_mul_lo_u32 v78, v140, s67
	v_cmp_lt_i32_e32 vcc, 0, v140
	v_add_lshl_u32 v78, v78, v6, 1
	v_add_u32_e32 v80, 0xfffff800, v77
	v_cndmask_b32_e32 v79, 0, v26, vcc
	v_cmp_gt_i32_e32 vcc, s77, v140
	s_waitcnt vmcnt(38)
	v_add_u32_e32 v93, v78, v79
	v_add_u32_e32 v77, 0x800, v77
	v_cndmask_b32_e32 v79, 0, v27, vcc
	v_add_u32_e32 v94, v78, v79
	v_add_u32_e32 v79, 0xfffff800, v78
	v_add_u32_e32 v95, 0x800, v78
	v_add_u32_e32 v96, 0xfffff800, v93
	v_add_u32_e32 v97, 0x800, v93
	v_add_u32_e32 v98, 0xfffff800, v94
	global_load_ushort v84, v80, s[72:73]
	global_load_ushort v83, v77, s[72:73]
	global_load_ushort v82, v79, s[72:73]
	global_load_ushort v81, v78, s[72:73]
	global_load_ushort v80, v95, s[72:73]
	global_load_ushort v79, v96, s[72:73]
	global_load_ushort v78, v93, s[72:73]
	global_load_ushort v77, v94, s[72:73]
	v_add_u32_e32 v93, 0x800, v94
	v_mul_lo_u32 v94, v139, s67
	v_cmp_lt_i32_e32 vcc, 0, v139
	v_add_lshl_u32 v94, v94, v6, 1
	s_waitcnt vmcnt(40)
	v_add_u32_e32 v117, 0x800, v94
	v_cndmask_b32_e32 v95, 0, v26, vcc
	v_cmp_gt_i32_e32 vcc, s77, v139
	s_waitcnt vmcnt(38)
	v_add_u32_e32 v115, v94, v95
	v_add_u32_e32 v118, 0xfffff800, v115
	v_cndmask_b32_e32 v95, 0, v27, vcc
	v_add_u32_e32 v116, v94, v95
	v_add_u32_e32 v95, 0xfffff800, v94
	v_add_u32_e32 v119, 0x800, v115
	v_add_u32_e32 v120, 0xfffff800, v116
	global_load_ushort v100, v97, s[72:73]
	global_load_ushort v99, v98, s[72:73]
	global_load_ushort v98, v93, s[72:73]
	global_load_ushort v97, v95, s[72:73]
	global_load_ushort v96, v94, s[72:73]
	global_load_ushort v95, v117, s[72:73]
	global_load_ushort v94, v115, s[72:73]
	global_load_ushort v93, v116, s[72:73]
	v_add_u32_e32 v115, 0x800, v116
	v_mul_lo_u32 v116, v138, s67
	v_cmp_lt_i32_e32 vcc, 0, v138
	v_add_lshl_u32 v116, v116, v6, 1
	s_waitcnt vmcnt(40)
	v_add_u32_e32 v125, 0x800, v116
	v_cndmask_b32_e32 v117, 0, v26, vcc
	v_cmp_gt_i32_e32 vcc, s77, v138
	s_waitcnt vmcnt(38)
	v_add_u32_e32 v123, v116, v117
	v_add_u32_e32 v126, 0xfffff800, v123
	v_cndmask_b32_e32 v117, 0, v27, vcc
	v_add_u32_e32 v124, v116, v117
	v_add_u32_e32 v117, 0xfffff800, v116
	v_add_u32_e32 v127, 0x800, v123
	s_waitcnt vmcnt(32)
	v_add_u32_e32 v129, 0xfffff800, v124
	global_load_ushort v122, v118, s[72:73]
	global_load_ushort v121, v119, s[72:73]
	global_load_ushort v120, v120, s[72:73]
	global_load_ushort v119, v115, s[72:73]
	global_load_ushort v118, v117, s[72:73]
	global_load_ushort v117, v116, s[72:73]
	global_load_ushort v116, v123, s[72:73]
	global_load_ushort v115, v124, s[72:73]
	v_add_u32_e32 v123, 0x800, v124
	v_mul_lo_u32 v124, v137, s67
	v_cmp_lt_i32_e32 vcc, 0, v137
	v_add_lshl_u32 v124, v124, v6, 1
	v_add_u32_e32 v134, 0xfffff800, v124
	v_cndmask_b32_e32 v128, 0, v26, vcc
	v_cmp_gt_i32_e32 vcc, s77, v137
	v_add_u32_e32 v132, v124, v128
	v_add_u32_e32 v135, 0x800, v124
	v_cndmask_b32_e32 v128, 0, v27, vcc
	v_add_u32_e32 v133, v124, v128
	global_load_ushort v131, v125, s[72:73]
	global_load_ushort v130, v126, s[72:73]
	global_load_ushort v128, v127, s[72:73]
	global_load_ushort v127, v129, s[72:73]
	global_load_ushort v126, v123, s[72:73]
	global_load_ushort v125, v124, s[72:73]
	global_load_ushort v124, v132, s[72:73]
	global_load_ushort v123, v133, s[72:73]
	v_add_u32_e32 v129, 0x800, v133
	v_add_u32_e32 v145, 0xfffff800, v132
	v_add_u32_e32 v147, 0x800, v132
	v_add_u32_e32 v148, 0xfffff800, v133
	global_load_ushort v136, v134, s[72:73]
	global_load_ushort v135, v135, s[72:73]
	global_load_ushort v134, v145, s[72:73]
	global_load_ushort v133, v147, s[72:73]
	global_load_ushort v132, v148, s[72:73]
	global_load_ushort v129, v129, s[72:73]
	s_waitcnt vmcnt(54)

; template <int RG, int NSW>
; __device__ __forceinline__ void scan_waves(const Params& p, float* lds, const int T, const int dir, const int wave, const int lane,
;                                            const size_t tok0, const int head, const int row_base) {
;     ...
;     lds_barrier();
.LBB0_1255:
	s_waitcnt lgkmcnt(0)
	s_barrier
	s_cmpk_gt_u32 s66, 0x3ff
	v_add_u32_e32 v145, 32, v142
	v_subrev_u32_e32 v147, 32, v141
	s_cbranch_scc1 .Lmy_w6_t2
	s_waitcnt vmcnt(46)
	v_add_u32_e32 v29, 32, v142
	v_subrev_u32_e32 v30, 32, v141
	v_cndmask_b32_e64 v29, v30, v29, s[0:1]
	v_cmp_lt_i32_e32 vcc, 0, v29
	v_mul_lo_u32 v30, v29, s67
	v_add_lshl_u32 v30, v30, v6, 1
	v_cndmask_b32_e32 v31, 0, v26, vcc
	v_cmp_gt_i32_e32 vcc, s77, v29
	v_add_u32_e32 v31, v30, v31
	v_add_u32_e32 v32, 0x800, v30
	v_cndmask_b32_e32 v29, 0, v27, vcc
	s_waitcnt vmcnt(38)
	v_add_u32_e32 v37, v30, v29
	v_add_u32_e32 v29, 0xfffff800, v30
	v_add_u32_e32 v33, 0xfffff800, v31
	v_add_u32_e32 v38, 0x800, v31
	v_add_u32_e32 v39, 0xfffff800, v37
	global_load_ushort v36, v29, s[72:73]
	global_load_ushort v35, v30, s[72:73]
	global_load_ushort v34, v32, s[72:73]
	global_load_ushort v33, v33, s[72:73]
	global_load_ushort v32, v31, s[72:73]
	global_load_ushort v31, v38, s[72:73]
	global_load_ushort v30, v39, s[72:73]
	global_load_ushort v29, v37, s[72:73]
	v_add_u32_e32 v38, 33, v142
	v_subrev_u32_e32 v39, 33, v141
	v_cndmask_b32_e64 v38, v39, v38, s[0:1]
	v_mul_lo_u32 v39, v38, s67
	v_cmp_lt_i32_e32 vcc, 0, v38
	v_add_lshl_u32 v39, v39, v6, 1
	v_add_u32_e32 v37, 0x800, v37
	v_cndmask_b32_e32 v40, 0, v26, vcc
	v_cmp_gt_i32_e32 vcc, s77, v38
	s_waitcnt vmcnt(38)
	v_add_u32_e32 v45, v39, v40
	v_add_u32_e32 v40, 0x800, v39
	v_cndmask_b32_e32 v38, 0, v27, vcc
	v_add_u32_e32 v46, v39, v38
	v_add_u32_e32 v38, 0xfffff800, v39
	v_add_u32_e32 v47, 0xfffff800, v45
	v_add_u32_e32 v48, 0x800, v45
	v_add_u32_e32 v49, 0xfffff800, v46
	global_load_ushort v44, v37, s[72:73]
	global_load_ushort v43, v38, s[72:73]
	global_load_ushort v42, v39, s[72:73]
	global_load_ushort v41, v40, s[72:73]
	global_load_ushort v40, v47, s[72:73]
	global_load_ushort v39, v45, s[72:73]
	global_load_ushort v38, v48, s[72:73]
	global_load_ushort v37, v46, s[72:73]
	v_add_u32_e32 v45, 0x800, v46
	v_add_u32_e32 v46, 34, v142
	v_subrev_u32_e32 v47, 34, v141
	v_cndmask_b32_e64 v46, v47, v46, s[0:1]
	v_mul_lo_u32 v47, v46, s67
	v_cmp_lt_i32_e32 vcc, 0, v46
	v_add_lshl_u32 v47, v47, v6, 1
	s_waitcnt vmcnt(27)
	v_subrev_u32_e32 v106, 37, v141
	v_cndmask_b32_e32 v48, 0, v26, vcc
	v_cmp_gt_i32_e32 vcc, s77, v46
	v_add_u32_e32 v69, v47, v48
	v_add_u32_e32 v48, 0x800, v47
	v_cndmask_b32_e32 v46, 0, v27, vcc
	v_add_u32_e32 v70, v47, v46
	v_add_u32_e32 v46, 0xfffff800, v47
	v_add_u32_e32 v71, 0xfffff800, v69
	v_add_u32_e32 v72, 0x800, v69
	v_add_u32_e32 v73, 0xfffff800, v70
	global_load_ushort v52, v49, s[72:73]
	global_load_ushort v51, v45, s[72:73]
	global_load_ushort v50, v46, s[72:73]
	global_load_ushort v49, v47, s[72:73]
	global_load_ushort v48, v48, s[72:73]
	global_load_ushort v47, v71, s[72:73]
	global_load_ushort v46, v69, s[72:73]
	global_load_ushort v45, v70, s[72:73]
	v_add_u32_e32 v69, 0x800, v70
	v_add_u32_e32 v70, 35, v142
	v_subrev_u32_e32 v71, 35, v141
	v_cndmask_b32_e64 v70, v71, v70, s[0:1]
	v_cmp_lt_i32_e32 vcc, 0, v70
	v_mul_lo_u32 v71, v70, s67
	v_add_lshl_u32 v71, v71, v6, 1
	v_cndmask_b32_e32 v74, 0, v26, vcc
	v_cmp_gt_i32_e32 vcc, s77, v70
	v_add_u32_e32 v85, v71, v74
	v_add_u32_e32 v87, 0x800, v71
	v_cndmask_b32_e32 v70, 0, v27, vcc
	v_add_u32_e32 v86, v71, v70
	v_add_u32_e32 v70, 0xfffff800, v71
	v_add_u32_e32 v88, 0xfffff800, v85
	v_add_u32_e32 v89, 0x800, v85
	v_add_u32_e32 v90, 0xfffff800, v86
	global_load_ushort v76, v72, s[72:73]
	global_load_ushort v75, v73, s[72:73]
	global_load_ushort v74, v69, s[72:73]
	global_load_ushort v73, v70, s[72:73]
	global_load_ushort v72, v71, s[72:73]
	global_load_ushort v71, v87, s[72:73]
	global_load_ushort v70, v85, s[72:73]
	global_load_ushort v69, v86, s[72:73]
	v_add_u32_e32 v85, 0x800, v86
	v_add_u32_e32 v86, 36, v142
	v_subrev_u32_e32 v87, 36, v141
	v_cndmask_b32_e64 v86, v87, v86, s[0:1]
	v_cmp_lt_i32_e32 vcc, 0, v86
	v_mul_lo_u32 v87, v86, s67
	v_add_lshl_u32 v87, v87, v6, 1
	v_cndmask_b32_e32 v91, 0, v26, vcc
	v_cmp_gt_i32_e32 vcc, s77, v86
	s_waitcnt vmcnt(38)
	v_add_u32_e32 v101, v87, v91
	v_add_u32_e32 v103, 0x800, v87
	v_cndmask_b32_e32 v86, 0, v27, vcc
	v_add_u32_e32 v102, v87, v86
	v_add_u32_e32 v86, 0xfffff800, v87
	v_add_u32_e32 v104, 0xfffff800, v101
	v_add_u32_e32 v105, 0x800, v101
	s_waitcnt vmcnt(32)
	v_add_u32_e32 v107, 0xfffff800, v102
	global_load_ushort v92, v88, s[72:73]
	global_load_ushort v91, v89, s[72:73]
	global_load_ushort v90, v90, s[72:73]
	global_load_ushort v89, v85, s[72:73]
	global_load_ushort v88, v86, s[72:73]
	global_load_ushort v87, v87, s[72:73]
	global_load_ushort v86, v101, s[72:73]
	global_load_ushort v85, v102, s[72:73]
	v_add_u32_e32 v101, 0x800, v102
	v_add_u32_e32 v102, 37, v142
	v_cndmask_b32_e64 v102, v106, v102, s[0:1]
	v_mul_lo_u32 v106, v102, s67
	v_cmp_lt_i32_e32 vcc, 0, v102
	v_add_lshl_u32 v110, v106, v6, 1
	v_add_u32_e32 v113, 0xfffff800, v110
	v_cndmask_b32_e32 v106, 0, v26, vcc
	v_cmp_gt_i32_e32 vcc, s77, v102
	v_add_u32_e32 v111, v110, v106
	v_add_u32_e32 v141, 0x800, v110
	v_cndmask_b32_e32 v102, 0, v27, vcc
	v_add_u32_e32 v112, v110, v102
	global_load_ushort v109, v103, s[72:73]
	global_load_ushort v108, v104, s[72:73]
	global_load_ushort v106, v105, s[72:73]
	global_load_ushort v105, v107, s[72:73]
	global_load_ushort v104, v101, s[72:73]
	global_load_ushort v103, v110, s[72:73]
	global_load_ushort v102, v111, s[72:73]
	global_load_ushort v101, v112, s[72:73]
	v_add_u32_e32 v107, 0x800, v112
	v_add_u32_e32 v142, 0xfffff800, v111
	v_add_u32_e32 v148, 0x800, v111
	v_add_u32_e32 v149, 0xfffff800, v112
	global_load_ushort v114, v113, s[72:73]
	global_load_ushort v113, v141, s[72:73]
	global_load_ushort v112, v142, s[72:73]
	global_load_ushort v111, v148, s[72:73]
	global_load_ushort v110, v149, s[72:73]
	global_load_ushort v107, v107, s[72:73]
	s_waitcnt vmcnt(54)

; template <int NS, bool LORA, int mat> ...
;     ...
;   const int colA = 3072 + mat * 128 + dir * 64 + fq * 8;
;   if (LORA) {
;     const u16* WT = (const u16*)(p.ws + (mat ? OFF_A2T : OFF_W2T)) + ((size_t)dir * 1024 + 64 * head + fr) * 64 + fq * 8;
; #pragma unroll
;     for (int nt = 0; nt < 4; ++nt) {
;       bw[nt][0] = *(const bf16x8*)(WT + nt * 16 * 64);
;       bw[nt][1] = *(const bf16x8*)(WT + nt * 16 * 64 + 32);
;       bias[nt] = (mat ? p.a0 : p.w0)[dir * 1024 + 64 * head + nt * 16 + fr];
;     }
; #pragma unroll
;     for (int j = 0; j < 8; ++j) { mu0[j] = p.mu_shift[colA + j]; mu1[j] = p.mu_shift[colA + 32 + j]; }
;   }
;   const int ch = 64 * head + lane;
;   const float kk_c = p.k_k[ch], ka_c = p.k_a[ch], rk_c = p.r_k[ch];
;   const float mu_r = p.mu_shift[ch], mu_k = p.mu_shift[1024 + ch], mu_v = p.mu_shift[2048 + ch];
.LBB0_1276:
	s_andn2_saveexec_b64 s[12:13], s[52:53]
	s_cbranch_execz .LBB0_1318
	s_waitcnt vmcnt(5)
	v_and_b32_e32 v114, 15, v140
	v_or_b32_e32 v0, s64, v114
	s_waitcnt vmcnt(4)
	v_mov_b32_e32 v1, s65
	v_lshrrev_b32_e32 v74, 4, v148
	v_lshlrev_b64 v[0:1], 7, v[0:1]
	v_lshl_or_b32 v40, v74, 3, s63
	v_lshl_add_u64 v[0:1], s[42:43], 0, v[0:1]
	v_and_b32_e32 v88, 48, v148
	v_mov_b32_e32 v89, 0
	v_lshl_add_u64 v[16:17], v[0:1], 0, v[88:89]
	s_movk_i32 s4, 0x1000
	v_lshlrev_b32_e32 v88, 2, v40
	v_add_co_u32_e32 v28, vcc, s4, v16
	v_or_b32_e32 v119, 0xc80, v40
	v_lshl_add_u64 v[40:41], s[38:39], 0, v[88:89]
	s_mov_b64 s[4:5], 0x3280
	v_or_b32_e32 v72, s61, v148
	v_or_b32_e32 v8, s62, v114
	v_addc_co_u32_e32 v29, vcc, 0, v17, vcc
	v_lshl_add_u64 v[44:45], v[40:41], 0, s[4:5]
	s_movk_i32 s4, 0x3000
	v_ashrrev_i32_e32 v73, 31, v72
	v_ashrrev_i32_e32 v9, 31, v8
	v_add_co_u32_e32 v40, vcc, s4, v40
	v_lshlrev_b64 v[48:49], 2, v[72:73]
	v_lshl_add_u64 v[32:33], v[8:9], 2, s[44:45]
	v_lshlrev_b32_e32 v36, 2, v119
	v_addc_co_u32_e32 v41, vcc, 0, v41, vcc
	v_lshl_add_u64 v[50:51], s[50:51], 0, v[48:49]
	global_load_dwordx4 v[0:3], v[16:17], off
	global_load_dwordx4 v[4:7], v[16:17], off offset:64
	global_load_dwordx4 v[8:11], v[16:17], off offset:2048
	global_load_dwordx4 v[12:15], v[16:17], off offset:2112
	global_load_dwordx4 v[16:19], v[28:29], off
	global_load_dwordx4 v[20:23], v[28:29], off offset:64
	global_load_dwordx4 v[24:27], v[28:29], off offset:2048
	global_load_dwordx4 v[28:31], v[28:29], off offset:2112
	global_load_dword v115, v[32:33], off
	global_load_dword v116, v[32:33], off offset:64
	global_load_dword v117, v[32:33], off offset:128
	global_load_dword v118, v[32:33], off offset:192
	global_load_dwordx4 v[32:35], v36, s[38:39]
	global_load_dwordx4 v[36:39], v36, s[38:39] offset:16
	global_load_dwordx4 v[40:43], v[40:41], off offset:640
	global_load_dwordx4 v[44:47], v[44:45], off offset:16
	s_movk_i32 s4, 0x2000
	global_load_dword v120, v[50:51], off
	v_lshl_add_u64 v[50:51], s[16:17], 0, v[48:49]
	global_load_dword v121, v[50:51], off
	v_lshl_add_u64 v[50:51], s[18:19], 0, v[48:49]
	v_lshl_add_u64 v[48:49], s[38:39], 0, v[48:49]
	global_load_dword v123, v[48:49], off
	v_add_co_u32_e32 v48, vcc, s4, v48
	s_movk_i32 s54, 0x3fff
	s_nop 0
	v_addc_co_u32_e32 v49, vcc, 0, v49, vcc
	global_load_dword v122, v[50:51], off
	global_load_dword v124, v[48:49], off offset:-4096
	global_load_dword v125, v[48:49], off
	v_bitop3_b32 v48, v140, s54, 15 bitop3:0x6c
	v_cndmask_b32_e64 v50, v48, v114, s[0:1]
	v_mul_u32_u24_e32 v48, 0xe00, v50
	v_mov_b32_e32 v126, 0xffffe400
	v_cmp_eq_u32_e32 vcc, 0, v50
	v_add_lshl_u32 v88, v119, v48, 1
	v_mov_b32_e32 v127, 0x1c00
	v_cndmask_b32_e64 v48, v126, 0, vcc
	v_cmp_eq_u32_e32 vcc, s54, v50
	v_add_u32_e32 v64, v88, v48
	v_lshl_add_u64 v[48:49], s[72:73], 0, v[88:89]
	v_cndmask_b32_e64 v50, v127, 0, vcc
	v_mov_b32_e32 v51, v89
	v_lshl_add_u64 v[68:69], v[48:49], 0, v[50:51]
	global_load_dwordx4 v[48:51], v64, s[72:73]
	global_load_dwordx4 v[52:55], v[68:69], off
	global_load_dwordx4 v[56:59], v88, s[72:73]
	global_load_dwordx4 v[60:63], v88, s[72:73] offset:64
	v_add_u32_e32 v64, 64, v64
	global_load_dwordx4 v[64:67], v64, s[72:73]
	global_load_dwordx4 v[68:71], v[68:69], off offset:64
	s_cmp_eq_u32 s3, 1
	s_cselect_b64 s[14:15], -1, 0
	s_cmp_eq_u32 s3, 2
	s_cselect_b64 s[42:43], -1, 0
	s_cmp_eq_u32 s3, 3
	v_lshl_add_u32 v73, v114, 2, 0
	v_add_u32_e32 v128, 0x400, v72
	v_lshlrev_b32_e32 v72, 10, v74
	s_mov_b32 s55, 2
	s_cselect_b64 s[44:45], -1, 0
	s_movk_i32 s56, 0xe00
	s_waitcnt vmcnt(28)
	v_lshl_add_u32 v129, v148, 2, 0
	v_cmp_eq_u32_e64 s[4:5], 0, v148
	v_sub_u32_e32 v130, 0, v114
	s_mov_b32 s57, -15
	s_movk_i32 s66, 0x400e
	v_add_u32_e32 v131, v73, v72
	v_mov_b32_e32 v132, 0
	v_mov_b32_e32 v133, 0
	v_mov_b32_e32 v134, 0
	v_mov_b32_e32 v135, 0
	v_mov_b32_e32 v136, 0
	v_mov_b32_e32 v137, 0
	v_mov_b32_e32 v138, 0
	v_mov_b32_e32 v139, 0
	v_mov_b32_e32 v145, 0
	v_mov_b32_e32 v148, 0
	v_mov_b32_e32 v150, 0
	v_mov_b32_e32 v152, 0
	v_mov_b32_e32 v153, 0
	v_mov_b32_e32 v154, 0
	v_mov_b32_e32 v155, 0
	v_mov_b32_e32 v162, 0
	v_mov_b32_e32 v156, 0
	v_mov_b32_e32 v165, 0
	v_mov_b32_e32 v166, 0
	v_mov_b32_e32 v168, 0
	v_mov_b32_e32 v169, 0
	v_mov_b32_e32 v170, 0
	v_mov_b32_e32 v171, 0
	v_mov_b32_e32 v172, 0
	v_mov_b32_e32 v174, 0
	v_mov_b32_e32 v173, 0
	v_mov_b32_e32 v175, 0
	v_mov_b32_e32 v140, 0
	v_mov_b32_e32 v141, 0
	v_mov_b32_e32 v142, 0
	v_mov_b32_e32 v143, 0
	v_mov_b32_e32 v144, 0
	v_mov_b32_e32 v147, 0
	v_mov_b32_e32 v149, 0
	v_mov_b32_e32 v151, 0
	v_mov_b32_e32 v157, 0
	v_mov_b32_e32 v158, 0
	v_mov_b32_e32 v159, 0
	v_mov_b32_e32 v160, 0
	v_mov_b32_e32 v161, 0
	v_mov_b32_e32 v163, 0
	v_mov_b32_e32 v164, 0
	v_mov_b32_e32 v176, 0
	v_mov_b32_e32 v167, 0
	v_mov_b32_e32 v177, 0
	v_mov_b32_e32 v178, 0
	v_mov_b32_e32 v179, 0
	v_mov_b32_e32 v180, 0
	v_mov_b32_e32 v181, 0
	v_mov_b32_e32 v182, 0
	v_mov_b32_e32 v183, 0
	v_mov_b32_e32 v185, 0
	v_mov_b32_e32 v184, 0
	v_mov_b32_e32 v186, 0
	s_waitcnt vmcnt(0)
	s_branch .LBB0_1280

.LBB0_1280:
	s_add_i32 s6, s55, -1
	s_cmpk_lt_u32 s6, 0x400
	v_add_u32_e32 v189, s66, v130
	s_cselect_b64 s[52:53], -1, 0
	s_cmpk_gt_u32 s6, 0x3ff
	v_add3_u32 v187, v114, s57, 31
	v_subrev_u32_e32 v188, 31, v189
	s_cbranch_scc1 .LBB0_1282
	v_cndmask_b32_e64 v74, v188, v187, s[0:1]
	v_mul_lo_u32 v72, v74, s56
	v_cmp_eq_u32_e32 vcc, 0, v74
	v_add_lshl_u32 v88, v72, v119, 1
	v_mov_b32_e32 v75, v89
	v_cndmask_b32_e64 v72, v126, 0, vcc
	v_add_u32_e32 v76, v88, v72
	v_cmp_gt_u32_e32 vcc, s54, v74
	v_lshl_add_u64 v[72:73], s[72:73], 0, v[88:89]
	global_load_dwordx4 v[226:229], v76, s[72:73]
	v_cndmask_b32_e32 v74, 0, v127, vcc
	v_lshl_add_u64 v[72:73], v[72:73], 0, v[74:75]
	v_add_u32_e32 v74, 64, v76
	global_load_dwordx4 v[230:233], v[72:73], off offset:64
	global_load_dwordx4 v[234:237], v74, s[72:73]
	global_load_dwordx4 v[238:241], v[72:73], off
	global_load_dwordx4 v[72:75], v88, s[72:73]
	global_load_dwordx4 v[76:79], v88, s[72:73] offset:64
	s_branch .LBB0_1283

.LBB0_1283:
	s_add_i32 s67, s55, -2
	s_cmpk_lt_u32 s67, 0x400
	s_cselect_b64 s[8:9], -1, 0
	s_cmpk_gt_u32 s67, 0x3ff
	s_cbranch_scc1 .LBB0_1285
	s_add_i32 s10, s57, 16
	s_add_i32 s11, s66, -16
	s_and_b64 s[6:7], s[0:1], exec
	s_cselect_b32 s6, s10, s11
	s_mulk_i32 s6, 0xe00
	s_add_i32 s10, s57, 17
	s_sub_i32 s11, s66, 17
	v_add_lshl_u32 v88, s6, v128, 1
	s_and_b64 s[6:7], s[0:1], exec
	s_cselect_b32 s6, s10, s11
	s_mulk_i32 s6, 0xe00
	s_add_i32 s10, s57, 18
	s_sub_i32 s11, s66, 18
	v_add_lshl_u32 v162, s6, v128, 1
	s_and_b64 s[6:7], s[0:1], exec
	s_cselect_b32 s6, s10, s11
	s_mulk_i32 s6, 0xe00
	v_add_u32_e32 v136, 0xffffe400, v88
	v_add_u32_e32 v139, 0x1c00, v88
	v_add_u32_e32 v132, 0xfffff800, v88
	v_add_u32_e32 v134, 0x800, v88
	v_add_u32_e32 v135, 0xffffdc00, v88
	v_add_u32_e32 v137, 0xffffec00, v88
	v_add_u32_e32 v138, 0x1400, v88
	v_add_lshl_u32 v172, s6, v128, 1
	global_load_ushort v132, v132, s[72:73]
	global_load_ushort v133, v88, s[72:73]
	global_load_ushort v134, v134, s[72:73]
	global_load_ushort v135, v135, s[72:73]
	global_load_ushort v136, v136, s[72:73]
	global_load_ushort v137, v137, s[72:73]
	global_load_ushort v138, v138, s[72:73]
	global_load_ushort v139, v139, s[72:73]
	v_add_u32_e32 v88, 0x2400, v88
	v_add_u32_e32 v154, 0xffffe400, v162
	v_add_u32_e32 v156, 0x1c00, v162
	v_add_u32_e32 v148, 0xfffff800, v162
	v_add_u32_e32 v152, 0x800, v162
	v_add_u32_e32 v153, 0xffffdc00, v162
	v_add_u32_e32 v155, 0xffffec00, v162
	v_add_u32_e32 v165, 0x1400, v162
	v_add_u32_e32 v171, 0xffffe400, v172
	v_add_u32_e32 v173, 0x1c00, v172
	v_add_u32_e32 v166, 0xfffff800, v172
	v_add_u32_e32 v169, 0x800, v172
	v_add_u32_e32 v170, 0xffffdc00, v172
	global_load_ushort v145, v88, s[72:73]
	global_load_ushort v148, v148, s[72:73]
	global_load_ushort v150, v162, s[72:73]
	global_load_ushort v152, v152, s[72:73]
	global_load_ushort v153, v153, s[72:73]
	global_load_ushort v154, v154, s[72:73]
	global_load_ushort v155, v155, s[72:73]
	global_load_ushort v156, v156, s[72:73]
	v_add_u32_e32 v88, 0x2400, v162
	global_load_ushort v162, v165, s[72:73]
	global_load_ushort v165, v88, s[72:73]
	global_load_ushort v166, v166, s[72:73]
	global_load_ushort v168, v172, s[72:73]
	global_load_ushort v169, v169, s[72:73]
	global_load_ushort v170, v170, s[72:73]
	global_load_ushort v171, v171, s[72:73]
	global_load_ushort v173, v173, s[72:73]
	v_add_u32_e32 v174, 0xffffec00, v172
	v_add_u32_e32 v175, 0x1400, v172
	v_add_u32_e32 v88, 0x2400, v172
	global_load_ushort v172, v174, s[72:73]
	global_load_ushort v174, v175, s[72:73]
	global_load_ushort v175, v88, s[72:73]

.LBB0_1300:
	s_waitcnt lgkmcnt(0)
	s_barrier
	s_cmpk_gt_u32 s55, 0x3ff
	s_cbranch_scc1 .LBB0_1302
	v_add3_u32 v48, v114, s57, 47
	v_subrev_u32_e32 v49, 47, v189
	v_cndmask_b32_e64 v50, v49, v48, s[0:1]
	v_mul_lo_u32 v48, v50, s56
	v_cmp_eq_u32_e32 vcc, 0, v50
	v_add_lshl_u32 v88, v48, v119, 1
	v_mov_b32_e32 v51, v89
	v_cndmask_b32_e64 v48, v126, 0, vcc
	v_cmp_gt_u32_e32 vcc, s54, v50
	v_add_u32_e32 v64, v88, v48
	v_lshl_add_u64 v[48:49], s[72:73], 0, v[88:89]
	v_cndmask_b32_e32 v50, 0, v127, vcc
	v_lshl_add_u64 v[68:69], v[48:49], 0, v[50:51]
	global_load_dwordx4 v[48:51], v64, s[72:73]
	global_load_dwordx4 v[52:55], v[68:69], off
	global_load_dwordx4 v[56:59], v88, s[72:73]
	global_load_dwordx4 v[60:63], v88, s[72:73] offset:64
	v_add_u32_e32 v64, 64, v64
	global_load_dwordx4 v[64:67], v64, s[72:73]
	global_load_dwordx4 v[68:71], v[68:69], off offset:64
.LBB0_1302:
	v_cndmask_b32_e64 v88, 0, 1, s[52:53]
	v_cmp_ne_u32_e64 s[10:11], 1, v88
	s_andn2_b64 vcc, exec, s[52:53]
	s_cbranch_vccnz .LBB0_1304
	s_add_i32 s77, s57, 32
	s_sub_i32 s80, s66, 32
	s_and_b64 s[52:53], s[0:1], exec
	s_cselect_b32 s52, s77, s80
	s_mulk_i32 s52, 0xe00
	s_add_i32 s77, s57, 33
	s_sub_i32 s80, s66, 33
	v_add_lshl_u32 v88, s52, v128, 1
	s_and_b64 s[52:53], s[0:1], exec
	s_cselect_b32 s52, s77, s80
	s_mulk_i32 s52, 0xe00
	s_add_i32 s77, s57, 34
	s_sub_i32 s80, s66, 34
	v_add_lshl_u32 v176, s52, v128, 1
	s_and_b64 s[52:53], s[0:1], exec
	s_cselect_b32 s52, s77, s80
	s_mulk_i32 s52, 0xe00
	v_add_u32_e32 v144, 0xffffe400, v88
	v_add_u32_e32 v151, 0x1c00, v88
	v_add_u32_e32 v140, 0xfffff800, v88
	v_add_u32_e32 v142, 0x800, v88
	v_add_u32_e32 v143, 0xffffdc00, v88
	v_add_u32_e32 v147, 0xffffec00, v88
	v_add_u32_e32 v149, 0x1400, v88
	v_add_lshl_u32 v183, s52, v128, 1
	global_load_ushort v140, v140, s[72:73]
	global_load_ushort v141, v88, s[72:73]
	global_load_ushort v142, v142, s[72:73]
	global_load_ushort v143, v143, s[72:73]
	global_load_ushort v144, v144, s[72:73]
	global_load_ushort v147, v147, s[72:73]
	global_load_ushort v149, v149, s[72:73]
	global_load_ushort v151, v151, s[72:73]
	v_add_u32_e32 v88, 0x2400, v88
	v_add_u32_e32 v163, 0xffffe400, v176
	v_add_u32_e32 v167, 0x1c00, v176
	v_add_u32_e32 v158, 0xfffff800, v176
	v_add_u32_e32 v160, 0x800, v176
	v_add_u32_e32 v161, 0xffffdc00, v176
	v_add_u32_e32 v164, 0xffffec00, v176
	v_add_u32_e32 v177, 0x1400, v176
	v_add_u32_e32 v182, 0xffffe400, v183
	v_add_u32_e32 v184, 0x1c00, v183
	v_add_u32_e32 v178, 0xfffff800, v183
	v_add_u32_e32 v180, 0x800, v183
	v_add_u32_e32 v181, 0xffffdc00, v183
	global_load_ushort v157, v88, s[72:73]
	global_load_ushort v158, v158, s[72:73]
	global_load_ushort v159, v176, s[72:73]
	global_load_ushort v160, v160, s[72:73]
	global_load_ushort v161, v161, s[72:73]
	global_load_ushort v163, v163, s[72:73]
	global_load_ushort v164, v164, s[72:73]
	global_load_ushort v167, v167, s[72:73]
	v_add_u32_e32 v88, 0x2400, v176
	global_load_ushort v176, v177, s[72:73]
	global_load_ushort v177, v88, s[72:73]
	global_load_ushort v178, v178, s[72:73]
	global_load_ushort v179, v183, s[72:73]
	global_load_ushort v180, v180, s[72:73]
	global_load_ushort v181, v181, s[72:73]
	global_load_ushort v182, v182, s[72:73]
	global_load_ushort v184, v184, s[72:73]
	v_add_u32_e32 v185, 0xffffec00, v183
	v_add_u32_e32 v186, 0x1400, v183
	v_add_u32_e32 v88, 0x2400, v183
	global_load_ushort v183, v185, s[72:73]
	global_load_ushort v185, v186, s[72:73]
	global_load_ushort v186, v88, s[72:73]

.LBB0_1323:
	s_add_i32 s6, s36, -1
	s_cmpk_lt_u32 s6, 0x400
	v_add_u32_e32 v149, s41, v147
	s_cselect_b64 s[16:17], -1, 0
	s_cmpk_gt_u32 s6, 0x3ff
	v_add3_u32 v11, v128, s40, 32
	v_subrev_u32_e32 v148, 32, v149
	s_cbranch_scc1 .LBB0_1325
	v_cndmask_b32_e64 v90, v148, v11, s[0:1]
	v_mul_lo_u32 v0, v90, s37
	v_cmp_eq_u32_e32 vcc, 0, v90
	v_add_lshl_u32 v0, v0, v133, 1
	v_lshl_add_u64 v[16:17], s[72:73], 0, v[0:1]
	v_cndmask_b32_e64 v12, v140, 0, vcc
	v_add_u32_e32 v92, v0, v12
	v_cmp_gt_u32_e32 vcc, s18, v90
	global_load_dwordx4 v[180:183], v92, s[72:73]
	v_mov_b32_e32 v91, v1
	v_cndmask_b32_e32 v90, 0, v141, vcc
	v_lshl_add_u64 v[16:17], v[16:17], 0, v[90:91]
	v_add_u32_e32 v90, 64, v92
	global_load_dwordx4 v[184:187], v90, s[72:73]
	global_load_dwordx4 v[188:191], v[16:17], off offset:64
	global_load_dwordx4 v[192:195], v[16:17], off
	global_load_dwordx4 v[94:97], v0, s[72:73]
	global_load_dwordx4 v[98:101], v0, s[72:73] offset:64
	s_branch .LBB0_1326

.LBB0_1326:
	s_add_i32 s44, s36, -2
	s_cmpk_lt_u32 s44, 0x400
	s_cselect_b64 s[8:9], -1, 0
	s_cmpk_gt_u32 s44, 0x3ff
	s_cbranch_scc1 .LBB0_1328
	s_add_i32 s10, s40, 16
	s_add_i32 s11, s41, -16
	s_and_b64 s[6:7], s[0:1], exec
	s_cselect_b32 s6, s10, s11
	s_mul_i32 s7, s6, 0xe00
	s_cmp_eq_u32 s6, 0
	v_add_lshl_u32 v0, s7, v142, 1
	s_cselect_b32 s7, 0, 0xffffe400
	s_cmpk_lt_u32 s6, 0x3fff
	s_cselect_b32 s6, 0x1c00, 0
	v_add_u32_e32 v2, s7, v0
	v_add_u32_e32 v3, s6, v0
	v_add_u32_e32 v4, 0xfffff800, v0
	v_add_u32_e32 v5, 0x800, v0
	v_add_u32_e32 v102, 0xfffff800, v2
	v_add_u32_e32 v103, 0x800, v2
	v_add_u32_e32 v104, 0xfffff800, v3
	global_load_ushort v196, v4, s[72:73]
	global_load_ushort v197, v0, s[72:73]
	global_load_ushort v198, v5, s[72:73]
	global_load_ushort v199, v102, s[72:73]
	global_load_ushort v200, v2, s[72:73]
	global_load_ushort v201, v103, s[72:73]
	global_load_ushort v202, v104, s[72:73]
	global_load_ushort v203, v3, s[72:73]
	v_add_u32_e32 v2, 0x800, v3
	global_load_ushort v204, v2, s[72:73]

.LBB0_1335:
	s_waitcnt lgkmcnt(0)
	s_barrier
	s_cmpk_gt_u32 s36, 0x3ff
	s_cbranch_scc1 .LBB0_1337
	v_add3_u32 v0, v128, s40, 48
	v_subrev_u32_e32 v66, 48, v149
	v_cndmask_b32_e64 v68, v66, v0, s[0:1]
	v_mul_lo_u32 v0, v68, s37
	v_cmp_eq_u32_e32 vcc, 0, v68
	v_add_lshl_u32 v0, v0, v133, 1
	v_mov_b32_e32 v69, v1
	v_cndmask_b32_e64 v66, v140, 0, vcc
	v_cmp_gt_u32_e32 vcc, s18, v68
	v_add_u32_e32 v82, v0, v66
	v_lshl_add_u64 v[66:67], s[72:73], 0, v[0:1]
	v_cndmask_b32_e32 v68, 0, v141, vcc
	v_lshl_add_u64 v[86:87], v[66:67], 0, v[68:69]
	global_load_dwordx4 v[66:69], v82, s[72:73]
	global_load_dwordx4 v[70:73], v[86:87], off
	global_load_dwordx4 v[74:77], v0, s[72:73]
	global_load_dwordx4 v[78:81], v0, s[72:73] offset:64
	v_add_u32_e32 v0, 64, v82
	global_load_dwordx4 v[82:85], v0, s[72:73]
	global_load_dwordx4 v[86:89], v[86:87], off offset:64
.LBB0_1337:
	v_cndmask_b32_e64 v0, 0, 1, s[16:17]
	v_cmp_ne_u32_e64 s[10:11], 1, v0
	s_andn2_b64 vcc, exec, s[16:17]
	s_cbranch_vccnz .LBB0_1339
	s_add_i32 s45, s40, 32
	s_sub_i32 s48, s41, 32
	s_and_b64 s[16:17], s[0:1], exec
	s_cselect_b32 s16, s45, s48
	s_mulk_i32 s16, 0xe00
	v_add_lshl_u32 v0, s16, v142, 1
	v_add_u32_e32 v8, 0x1c00, v0
	v_add_u32_e32 v9, 0x800, v0
	v_add_u32_e32 v10, 0xffffdc00, v0
	v_add_u32_e32 v102, 0xffffec00, v0
	v_add_u32_e32 v103, 0x1400, v0
	v_add_u32_e32 v7, 0xffffe400, v0
	global_load_ushort v196, v9, s[72:73]
	global_load_ushort v197, v10, s[72:73]
	global_load_ushort v198, v102, s[72:73]
	global_load_ushort v199, v103, s[72:73]
	global_load_ushort v200, v8, s[72:73]
	v_add_u32_e32 v10, 0x2400, v0
	v_add_u32_e32 v103, 0xfffff800, v0
	global_load_ushort v201, v10, s[72:73]
	global_load_ushort v202, v7, s[72:73]
	global_load_ushort v203, v0, s[72:73]
	global_load_ushort v204, v103, s[72:73]

; __device__ __forceinline__ void tr_job(float* lds, int& gt, const float* __restrict__ src, int src_ld, const float* __restrict__ gain,
;                        u16* __restrict__ dst, int dst_ld, int K, int Nvalid, int Ndst) {
;     ...
;     for (int u = 0; u < 32; ++u) {
;       const int k = 2 * u + half, gk = k0 + k;
;       const int gkc = gk < K ? gk : K - 1;
;       float v = src[(size_t)gkc * src_ld + gnc];
;       if (gain) v *= gain[gkc];
.LBB0_1393:
	v_add_u32_e32 v8, s6, v3
	s_and_b64 vcc, exec, s[0:1]
	s_cbranch_vccnz .Lmy_trd_nog
	v_ashrrev_i32_e32 v9, 31, v8
	v_lshl_add_u64 v[18:19], v[8:9], 2, s[26:27]
	global_load_dword v216, v[18:19], off
	global_load_dword v217, v[18:19], off offset:8
	global_load_dword v218, v[18:19], off offset:16
	global_load_dword v219, v[18:19], off offset:24
	global_load_dword v220, v[18:19], off offset:32
	global_load_dword v221, v[18:19], off offset:40
	global_load_dword v222, v[18:19], off offset:48
	global_load_dword v223, v[18:19], off offset:56
	global_load_dword v224, v[18:19], off offset:64
	global_load_dword v225, v[18:19], off offset:72
	global_load_dword v226, v[18:19], off offset:80
	global_load_dword v227, v[18:19], off offset:88
	global_load_dword v228, v[18:19], off offset:96
	global_load_dword v229, v[18:19], off offset:104
	global_load_dword v230, v[18:19], off offset:112
	global_load_dword v231, v[18:19], off offset:120
	s_branch .Lmy_trd_data

; __device__ __forceinline__ void tr_job(float* lds, int& gt, const float* __restrict__ src, int src_ld, const float* __restrict__ gain,
;                        u16* __restrict__ dst, int dst_ld, int K, int Nvalid, int Ndst) {
;     ...
; #pragma unroll 16
;     for (int u = 0; u < 32; ++u) {
;       const int k = 2 * u + half, gk = k0 + k;
;       const int gkc = gk < K ? gk : K - 1;
;       float v = src[(size_t)gkc * src_ld + gnc];
;       if (gain) v *= gain[gkc];
;       wl[k * 33 + c] = (gk < K && gn < Nvalid) ? v : 0.f;
;     }
.Lmy_trd_data:
	v_mad_i64_i32 v[18:19], s[36:37], v8, s22, v[4:5]
	global_load_dword v200, v[18:19], off
	v_add_u32_e32 v9, 2, v8
	v_mad_i64_i32 v[18:19], s[36:37], v9, s22, v[4:5]
	global_load_dword v201, v[18:19], off
	v_add_u32_e32 v9, 4, v8
	v_mad_i64_i32 v[18:19], s[36:37], v9, s22, v[4:5]
	global_load_dword v202, v[18:19], off
	v_add_u32_e32 v9, 6, v8
	v_mad_i64_i32 v[18:19], s[36:37], v9, s22, v[4:5]
	global_load_dword v203, v[18:19], off
	v_add_u32_e32 v9, 8, v8
	v_mad_i64_i32 v[18:19], s[36:37], v9, s22, v[4:5]
	global_load_dword v204, v[18:19], off
	v_add_u32_e32 v9, 10, v8
	v_mad_i64_i32 v[18:19], s[36:37], v9, s22, v[4:5]
	global_load_dword v205, v[18:19], off
	v_add_u32_e32 v9, 12, v8
	v_mad_i64_i32 v[18:19], s[36:37], v9, s22, v[4:5]
	global_load_dword v206, v[18:19], off
	v_add_u32_e32 v9, 14, v8
	v_mad_i64_i32 v[18:19], s[36:37], v9, s22, v[4:5]
	global_load_dword v207, v[18:19], off
	v_add_u32_e32 v9, 16, v8
	v_mad_i64_i32 v[18:19], s[36:37], v9, s22, v[4:5]
	global_load_dword v208, v[18:19], off
	v_add_u32_e32 v9, 18, v8
	v_mad_i64_i32 v[18:19], s[36:37], v9, s22, v[4:5]
	global_load_dword v209, v[18:19], off
	v_add_u32_e32 v9, 20, v8
	v_mad_i64_i32 v[18:19], s[36:37], v9, s22, v[4:5]
	global_load_dword v210, v[18:19], off
	v_add_u32_e32 v9, 22, v8
	v_mad_i64_i32 v[18:19], s[36:37], v9, s22, v[4:5]
	global_load_dword v211, v[18:19], off
	v_add_u32_e32 v9, 24, v8
	v_mad_i64_i32 v[18:19], s[36:37], v9, s22, v[4:5]
	global_load_dword v212, v[18:19], off
	v_add_u32_e32 v9, 26, v8
	v_mad_i64_i32 v[18:19], s[36:37], v9, s22, v[4:5]
	global_load_dword v213, v[18:19], off
	v_add_u32_e32 v9, 28, v8
	v_mad_i64_i32 v[18:19], s[36:37], v9, s22, v[4:5]
	global_load_dword v214, v[18:19], off
	v_add_u32_e32 v9, 30, v8
	v_mad_i64_i32 v[18:19], s[36:37], v9, s22, v[4:5]
	global_load_dword v215, v[18:19], off
	s_waitcnt vmcnt(15)
	v_mul_f32_e32 v200, v200, v216
	v_cndmask_b32_e64 v200, 0, v200, s[4:5]
	ds_write_b32 v10, v200
	s_waitcnt vmcnt(14)
	v_mul_f32_e32 v201, v201, v217
	v_cndmask_b32_e64 v201, 0, v201, s[4:5]
	ds_write_b32 v10, v201 offset:264
	s_waitcnt vmcnt(13)
	v_mul_f32_e32 v202, v202, v218
	v_cndmask_b32_e64 v202, 0, v202, s[4:5]
	ds_write_b32 v10, v202 offset:528
	s_waitcnt vmcnt(12)
	v_mul_f32_e32 v203, v203, v219
	v_cndmask_b32_e64 v203, 0, v203, s[4:5]
	ds_write_b32 v10, v203 offset:792
	s_waitcnt vmcnt(11)
	v_mul_f32_e32 v204, v204, v220
	v_cndmask_b32_e64 v204, 0, v204, s[4:5]
	ds_write_b32 v10, v204 offset:1056
	s_waitcnt vmcnt(10)
	v_mul_f32_e32 v205, v205, v221
	v_cndmask_b32_e64 v205, 0, v205, s[4:5]
	ds_write_b32 v10, v205 offset:1320
	s_waitcnt vmcnt(9)
	v_mul_f32_e32 v206, v206, v222
	v_cndmask_b32_e64 v206, 0, v206, s[4:5]
	ds_write_b32 v10, v206 offset:1584
	s_waitcnt vmcnt(8)
	v_mul_f32_e32 v207, v207, v223
	v_cndmask_b32_e64 v207, 0, v207, s[4:5]
	ds_write_b32 v10, v207 offset:1848
	s_waitcnt vmcnt(7)
	v_mul_f32_e32 v208, v208, v224
	v_cndmask_b32_e64 v208, 0, v208, s[4:5]
	ds_write_b32 v10, v208 offset:2112
	s_waitcnt vmcnt(6)
	v_mul_f32_e32 v209, v209, v225
	v_cndmask_b32_e64 v209, 0, v209, s[4:5]
	ds_write_b32 v10, v209 offset:2376
	s_waitcnt vmcnt(5)
	v_mul_f32_e32 v210, v210, v226
	v_cndmask_b32_e64 v210, 0, v210, s[4:5]
	ds_write_b32 v10, v210 offset:2640
	s_waitcnt vmcnt(4)
	v_mul_f32_e32 v211, v211, v227
	v_cndmask_b32_e64 v211, 0, v211, s[4:5]
	ds_write_b32 v10, v211 offset:2904
	s_waitcnt vmcnt(3)
	v_mul_f32_e32 v212, v212, v228
	v_cndmask_b32_e64 v212, 0, v212, s[4:5]
	ds_write_b32 v10, v212 offset:3168
	s_waitcnt vmcnt(2)
	v_mul_f32_e32 v213, v213, v229
	v_cndmask_b32_e64 v213, 0, v213, s[4:5]
	ds_write_b32 v10, v213 offset:3432
	s_waitcnt vmcnt(1)
	v_mul_f32_e32 v214, v214, v230
	v_cndmask_b32_e64 v214, 0, v214, s[4:5]
	ds_write_b32 v10, v214 offset:3696
	s_waitcnt vmcnt(0)
	v_mul_f32_e32 v215, v215, v231
	v_cndmask_b32_e64 v215, 0, v215, s[4:5]
	ds_write_b32 v10, v215 offset:3960
	s_add_i32 s6, s6, 32
	v_add_u32_e32 v10, 0x1080, v10
	s_cmp_eq_u32 s6, 64
	s_cbranch_scc0 .LBB0_1393

; __device__ __forceinline__ void tr_job(float* lds, int& gt, const float* __restrict__ src, int src_ld, const float* __restrict__ gain,
;                        u16* __restrict__ dst, int dst_ld, int K, int Nvalid, int Ndst) {
;     ...
; #pragma unroll 16
;     for (int u = 0; u < 32; ++u) {
;       const int k = 2 * u + half, gk = k0 + k;
;       const int gkc = gk < K ? gk : K - 1;
;       float v = src[(size_t)gkc * src_ld + gnc];
;       if (gain) v *= gain[gkc];
;       wl[k * 33 + c] = (gk < K && gn < Nvalid) ? v : 0.f;
;     }
.Lmy_tre_data:
	v_mad_i64_i32 v[18:19], s[28:29], v8, s22, v[4:5]
	global_load_dword v200, v[18:19], off
	v_add_u32_e32 v9, 2, v8
	v_mad_i64_i32 v[18:19], s[28:29], v9, s22, v[4:5]
	global_load_dword v201, v[18:19], off
	v_add_u32_e32 v9, 4, v8
	v_mad_i64_i32 v[18:19], s[28:29], v9, s22, v[4:5]
	global_load_dword v202, v[18:19], off
	v_add_u32_e32 v9, 6, v8
	v_mad_i64_i32 v[18:19], s[28:29], v9, s22, v[4:5]
	global_load_dword v203, v[18:19], off
	v_add_u32_e32 v9, 8, v8
	v_mad_i64_i32 v[18:19], s[28:29], v9, s22, v[4:5]
	global_load_dword v204, v[18:19], off
	v_add_u32_e32 v9, 10, v8
	v_mad_i64_i32 v[18:19], s[28:29], v9, s22, v[4:5]
	global_load_dword v205, v[18:19], off
	v_add_u32_e32 v9, 12, v8
	v_mad_i64_i32 v[18:19], s[28:29], v9, s22, v[4:5]
	global_load_dword v206, v[18:19], off
	v_add_u32_e32 v9, 14, v8
	v_mad_i64_i32 v[18:19], s[28:29], v9, s22, v[4:5]
	global_load_dword v207, v[18:19], off
	v_add_u32_e32 v9, 16, v8
	v_mad_i64_i32 v[18:19], s[28:29], v9, s22, v[4:5]
	global_load_dword v208, v[18:19], off
	v_add_u32_e32 v9, 18, v8
	v_mad_i64_i32 v[18:19], s[28:29], v9, s22, v[4:5]
	global_load_dword v209, v[18:19], off
	v_add_u32_e32 v9, 20, v8
	v_mad_i64_i32 v[18:19], s[28:29], v9, s22, v[4:5]
	global_load_dword v210, v[18:19], off
	v_add_u32_e32 v9, 22, v8
	v_mad_i64_i32 v[18:19], s[28:29], v9, s22, v[4:5]
	global_load_dword v211, v[18:19], off
	v_add_u32_e32 v9, 24, v8
	v_mad_i64_i32 v[18:19], s[28:29], v9, s22, v[4:5]
	global_load_dword v212, v[18:19], off
	v_add_u32_e32 v9, 26, v8
	v_mad_i64_i32 v[18:19], s[28:29], v9, s22, v[4:5]
	global_load_dword v213, v[18:19], off
	v_add_u32_e32 v9, 28, v8
	v_mad_i64_i32 v[18:19], s[28:29], v9, s22, v[4:5]
	global_load_dword v214, v[18:19], off
	v_add_u32_e32 v9, 30, v8
	v_mad_i64_i32 v[18:19], s[28:29], v9, s22, v[4:5]
	global_load_dword v215, v[18:19], off
	s_waitcnt vmcnt(15)
	v_mul_f32_e32 v200, v200, v216
	v_cndmask_b32_e64 v200, 0, v200, s[4:5]
	ds_write_b32 v10, v200
	s_waitcnt vmcnt(14)
	v_mul_f32_e32 v201, v201, v217
	v_cndmask_b32_e64 v201, 0, v201, s[4:5]
	ds_write_b32 v10, v201 offset:264
	s_waitcnt vmcnt(13)
	v_mul_f32_e32 v202, v202, v218
	v_cndmask_b32_e64 v202, 0, v202, s[4:5]
	ds_write_b32 v10, v202 offset:528
	s_waitcnt vmcnt(12)
	v_mul_f32_e32 v203, v203, v219
	v_cndmask_b32_e64 v203, 0, v203, s[4:5]
	ds_write_b32 v10, v203 offset:792
	s_waitcnt vmcnt(11)
	v_mul_f32_e32 v204, v204, v220
	v_cndmask_b32_e64 v204, 0, v204, s[4:5]
	ds_write_b32 v10, v204 offset:1056
	s_waitcnt vmcnt(10)
	v_mul_f32_e32 v205, v205, v221
	v_cndmask_b32_e64 v205, 0, v205, s[4:5]
	ds_write_b32 v10, v205 offset:1320
	s_waitcnt vmcnt(9)
	v_mul_f32_e32 v206, v206, v222
	v_cndmask_b32_e64 v206, 0, v206, s[4:5]
	ds_write_b32 v10, v206 offset:1584
	s_waitcnt vmcnt(8)
	v_mul_f32_e32 v207, v207, v223
	v_cndmask_b32_e64 v207, 0, v207, s[4:5]
	ds_write_b32 v10, v207 offset:1848
	s_waitcnt vmcnt(7)
	v_mul_f32_e32 v208, v208, v224
	v_cndmask_b32_e64 v208, 0, v208, s[4:5]
	ds_write_b32 v10, v208 offset:2112
	s_waitcnt vmcnt(6)
	v_mul_f32_e32 v209, v209, v225
	v_cndmask_b32_e64 v209, 0, v209, s[4:5]
	ds_write_b32 v10, v209 offset:2376
	s_waitcnt vmcnt(5)
	v_mul_f32_e32 v210, v210, v226
	v_cndmask_b32_e64 v210, 0, v210, s[4:5]
	ds_write_b32 v10, v210 offset:2640
	s_waitcnt vmcnt(4)
	v_mul_f32_e32 v211, v211, v227
	v_cndmask_b32_e64 v211, 0, v211, s[4:5]
	ds_write_b32 v10, v211 offset:2904
	s_waitcnt vmcnt(3)
	v_mul_f32_e32 v212, v212, v228
	v_cndmask_b32_e64 v212, 0, v212, s[4:5]
	ds_write_b32 v10, v212 offset:3168
	s_waitcnt vmcnt(2)
	v_mul_f32_e32 v213, v213, v229
	v_cndmask_b32_e64 v213, 0, v213, s[4:5]
	ds_write_b32 v10, v213 offset:3432
	s_waitcnt vmcnt(1)
	v_mul_f32_e32 v214, v214, v230
	v_cndmask_b32_e64 v214, 0, v214, s[4:5]
	ds_write_b32 v10, v214 offset:3696
	s_waitcnt vmcnt(0)
	v_mul_f32_e32 v215, v215, v231
	v_cndmask_b32_e64 v215, 0, v215, s[4:5]
	ds_write_b32 v10, v215 offset:3960
	s_add_i32 s6, s6, 32
	v_add_u32_e32 v10, 0x1080, v10
	s_cmp_eq_u32 s6, 64
	s_cbranch_scc0 .LBB0_1498
